# v86 + weight-conversion phase: small matrices assigned to disjoint wave ranges (max items per wave 13 -> 6)
# speedup vs baseline: 1.0199x; 1.0034x over previous
.LBB0_50:
	v_readlane_b32 s2, v253, 24
	s_add_i32 s2, s2, 768
	s_and_b32 s2, s2, 0x7ff
	v_writelane_b32 v255, s2, 52
	s_cmpk_lt_i32 s2, 0xc0
	s_cbranch_scc0 .LBB0_61
	s_load_dwordx2 s[2:3], s[0:1], 0x58
	s_load_dwordx2 s[10:11], s[0:1], 0x48
	v_readlane_b32 s14, v255, 25
	s_mul_i32 s9, s14, 0x120000
	s_mul_hi_u32 s8, s14, 0x120000
	s_mul_i32 s26, s14, 0x180
	s_waitcnt lgkmcnt(0)
	s_add_u32 s16, s2, s9
	s_addc_u32 s17, s3, s8
	s_lshl_b64 s[2:3], s[26:27], 2
	s_add_u32 s8, s10, s2
	v_ashrrev_i32_e32 v62, 3, v43
	s_movk_i32 s2, 0x84
	v_mov_b32_e32 v45, v1
	s_addc_u32 s9, s11, s3
	v_mul_lo_u32 v4, v62, s2
	v_lshl_add_u64 v[2:3], s[6:7], 0, v[44:45]
	s_mov_b64 s[2:3], 0x1600000
	v_readlane_b32 s15, v255, 26
	v_readlane_b32 s14, v253, 13
	v_mul_u32_u24_e32 v5, 0x420, v61
	v_lshl_add_u64 v[46:47], v[2:3], 0, s[2:3]
	v_lshlrev_b32_e32 v2, 2, v62
	s_cmp_lg_u64 s[10:11], 0
	v_add_u32_e32 v0, s14, v44
	v_add3_u32 v45, s14, v5, v2
	v_readlane_b32 s2, v255, 52
	v_readlane_b32 s14, v253, 9
	v_lshlrev_b32_e32 v57, 2, v61
	s_cselect_b64 s[10:11], -1, 0
	v_lshl_add_u32 v63, s2, 5, v62
	s_lshl_b32 s18, s14, 5
	v_add_u32_e32 v64, v0, v4
	s_mov_b32 s19, s2
	v_readlane_b32 s3, v253, 25
	v_readlane_b32 s15, v253, 10
	s_branch .LBB0_54

.LBB0_61:
	v_readlane_b32 s2, v253, 24
	s_add_i32 s2, s2, 512
	s_and_b32 s2, s2, 0x7ff
	v_writelane_b32 v255, s2, 52
	s_cmpk_lt_i32 s2, 0x80
	s_cselect_b64 vcc, 0, -1
	v_readlane_b32 s2, v255, 25
	v_readlane_b32 s3, v255, 26
	s_lshl_b64 s[8:9], s[2:3], 20
	s_cbranch_vccnz .LBB0_67
	s_load_dwordx2 s[2:3], s[0:1], 0x50
	s_load_dwordx2 s[14:15], s[0:1], 0x60
	v_readlane_b32 s10, v255, 25
	v_readlane_b32 s11, v255, 26
	s_lshl_b32 s26, s10, 8
	s_lshl_b64 s[10:11], s[26:27], 2
	s_waitcnt lgkmcnt(0)
	s_add_u32 s10, s2, s10
	s_addc_u32 s11, s3, s11
	s_add_u32 s16, s14, s8
	s_addc_u32 s17, s15, s9
	v_ashrrev_i32_e32 v41, 3, v43
	s_cmp_lg_u64 s[2:3], 0
	s_movk_i32 s2, 0x84
	v_mov_b32_e32 v45, v1
	v_mul_lo_u32 v4, v41, s2
	v_lshl_add_u64 v[2:3], s[6:7], 0, v[44:45]
	s_mov_b64 s[2:3], 0x1700000
	v_readlane_b32 s18, v253, 13
	v_mul_u32_u24_e32 v5, 0x420, v61
	v_lshl_add_u64 v[34:35], v[2:3], 0, s[2:3]
	v_lshlrev_b32_e32 v2, 2, v41
	v_add_u32_e32 v0, s18, v44
	v_add3_u32 v47, s18, v5, v2
	v_readlane_b32 s18, v253, 9
	v_lshl_add_u64 v[36:37], s[16:17], 0, v[44:45]
	v_readlane_b32 s16, v255, 52
	v_readlane_b32 s19, v253, 10
	s_cselect_b64 s[14:15], -1, 0
	s_lshl_b32 s2, s16, 3
	s_lshl_b32 s3, s18, 3
	v_lshl_add_u32 v45, s16, 5, v41
	s_lshl_b32 s18, s18, 5
	v_add_u32_e32 v51, v0, v4
	s_mov_b32 s19, s16
	v_readlane_b32 s17, v253, 25
	s_branch .LBB0_65

.LBB0_78:
	v_readlane_b32 s2, v253, 24
	s_lshl_b32 s3, s26, 8
	s_sub_i32 s2, s2, s3
	s_add_i32 s2, s2, 0x400
	s_and_b32 s2, s2, 0x7ff
	v_writelane_b32 v255, s2, 52
	s_cmpk_lt_i32 s2, 0x100
	s_cbranch_scc0 .LBB0_77
	s_lshl_b64 s[6:7], s[26:27], 20
	s_lshl_b64 s[2:3], s[26:27], 21
	v_lshl_add_u64 v[6:7], v[2:3], 0, s[6:7]
	v_readlane_b32 s6, v255, 52
	v_readlane_b32 s16, v253, 9
	v_lshl_add_u64 v[8:9], v[4:5], 0, s[2:3]
	s_lshl_b32 s2, s6, 5
	s_lshl_b32 s3, s16, 5
	s_mov_b32 s14, s6
	v_readlane_b32 s7, v253, 25
	v_readlane_b32 s17, v253, 10

.LBB0_81:
	v_readlane_b32 s2, v253, 24
	s_add_i32 s2, s2, 1536
	s_and_b32 s2, s2, 0x7ff
	v_writelane_b32 v255, s2, 52
	s_cmpk_lt_i32 s2, 0x200
	s_cbranch_scc0 .LBB0_84
	s_load_dwordx2 s[2:3], s[0:1], 0xb0
	s_lshl_b64 s[6:7], s[8:9], 2
	s_mov_b64 s[8:9], 0x1e00000
	v_lshl_add_u64 v[2:3], v[36:37], 0, s[8:9]
	v_readlane_b32 s8, v255, 52
	s_waitcnt lgkmcnt(0)
	s_add_u32 s6, s2, s6
	s_addc_u32 s7, s3, s7
	v_readlane_b32 s14, v253, 9
	s_lshl_b32 s2, s8, 5
	s_lshl_b32 s3, s14, 5
	v_lshl_add_u64 v[4:5], v[34:35], 2, s[6:7]
	s_mov_b32 s10, s8
	v_readlane_b32 s9, v253, 25
	v_readlane_b32 s15, v253, 10
